# peeled first iteration of MLP1/QKV/GLU K-loops: first counted wait vmcnt(8)->vmcnt(24) so the previous tile's epilogue stores need not drain before the first MFMA segment
# speedup vs baseline: 1.0020x; 1.0015x over previous
;     __device__ __forceinline__ const char* tile(const Unit& u, int t) const { return A + (size_t)u.pm * 2 * hstep() + (size_t)t * (BK * 2); }
;     __device__ __forceinline__ const char* tile(const Unit& u, int t) const { return U + (long)(t >> 2) * xoff + (size_t)u.pn * (1024 * 512) + (size_t)u.pm * 2 * hstep() + (size_t)(t & 3) * (BK * 2); }
; #define PG8_STAGE(bufoff, gbase, voff) do { _Pragma("unroll") for (int _i = 0; _i < 2; ++_i) \
;         __builtin_amdgcn_global_load_lds((const unsigned*)((const char*)(gbase) + (voff)[_i]), (PG8_LAS unsigned*)(lds + (bufoff) + ldsw + _i * 8192), 16, 0, 0); } while (0)
; #define PG8_LDA(dst, b, h) do { _Pragma("unroll") for (int m = 0; m < 4; ++m) _Pragma("unroll") for (int k = 0; k < 2; ++k) dst[m][k] = *(const PG8_LAS bf16x8*)(lds + PG8_SA(b, h) + aoff + m * 2048 + k * 1024); } while (0)
; #define PG8_LDB(dst, b, h) do { _Pragma("unroll") for (int n = 0; n < 2; ++n) _Pragma("unroll") for (int k = 0; k < 2; ++k) dst[n][k] = *(const PG8_LAS bf16x8*)(lds + PG8_SB(b, h) + boff + n * 2048 + k * 1024); } while (0)
; #define PG8_MMA(ai, bj, At, Bt) do { __builtin_amdgcn_s_setprio(1); _Pragma("unroll") for (int m = 0; m < 4; ++m) _Pragma("unroll") for (int n = 0; n < 2; ++n) _Pragma("unroll") for (int k = 0; k < 2; ++k) \
;         acc[ai][bj][m][n] = __builtin_amdgcn_mfma_f32_16x16x32_bf16(Bt[n][k], At[m][k], acc[ai][bj][m][n], 0, 0, 0); __builtin_amdgcn_s_setprio(0); } while (0)
; #define PG8_BAR __builtin_amdgcn_s_barrier()
;     ...
;         for (int t = 0; t < nt; t += 2) {
;             const bool last = (t == nt - 2);
;             const char* a1 = AS.tile(cur, t + 1);
;             const char* a2 = last ? AS.tile(nu, 0) : AS.tile(cur, t + 2); const char* b2 = last ? nB : cB + (size_t)(t + 2) * kstep;
;             const char* a3 = last ? AS.tile(nu, 1) : AS.tile(cur, t + 3); const char* b3 = b2 + kstep;
;             PG8_LDB(B0, 0, 0); PG8_LDB(B1, 0, 1); PG8_SCHED; PG8_LDA(At, 0, 0); PG8_STAGE(PG8_SA(1, 1), a1 + hstepA, voffA);
;             PG8_WAIT_V(8); PG8_WAIT_L(0); PG8_BAR; PG8_MMA(0, 0, At, B0); PG8_MMA(0, 1, At, B1); PG8_BAR; PG8_SCHED;
;             PG8_LDA(At, 0, 1); PG8_STAGE(PG8_SB(0, 0), b2, voffB); PG8_STAGE(PG8_SB(0, 1), b2 + hstepB, voffB); PG8_STAGE(PG8_SA(0, 0), a2, voffA);
;             PG8_WAIT_V(8); PG8_WAIT_L(0); PG8_BAR; PG8_MMA(1, 0, At, B0); PG8_MMA(1, 1, At, B1); PG8_BAR; PG8_SCHED;
.Lpeel_451:
	s_add_u32 s20, s61, s18
	s_addc_u32 s21, s64, s19
	s_add_u32 s26, s20, 0x3600100
	s_addc_u32 s27, s21, 0
	s_add_u32 s24, s65, s18
	s_addc_u32 s25, s66, s19
	s_add_u32 s20, s20, 0x3600180
	s_addc_u32 s21, s21, 0
	s_add_i32 s68, 0, 0x10000
	s_add_i32 s70, 0, 0x14000
	v_add_u32_e32 v144, s68, v203
	v_add_u32_e32 v174, s70, v203
	ds_read_b128 v[132:135], v144
	ds_read_b128 v[136:139], v144 offset:1024
	ds_read_b128 v[140:143], v144 offset:2048
	ds_read_b128 v[144:147], v144 offset:3072
	ds_read_b128 v[148:151], v174
	ds_read_b128 v[152:155], v174 offset:1024
	ds_read_b128 v[170:173], v174 offset:2048
	ds_read_b128 v[174:177], v174 offset:3072
	s_cmpk_eq_i32 s18, 0x700
	s_cselect_b32 s21, s60, s21
	s_cselect_b32 s20, s59, s20
	s_cselect_b32 s25, s57, s25
	s_cselect_b32 s24, s56, s24
	s_cselect_b32 s27, s58, s27
	s_cselect_b32 s26, s3, s26
	v_lshl_add_u64 v[238:239], v[112:113], 0, s[18:19]
	s_add_i32 m0, s35, 0xc000
	ds_read_b128 v[178:181], v211
	ds_read_b128 v[182:185], v211 offset:1024
	ds_read_b128 v[186:189], v211 offset:2048
	ds_read_b128 v[190:193], v211 offset:3072
	ds_read_b128 v[194:197], v211 offset:4096
	ds_read_b128 v[198:201], v211 offset:5120
	ds_read_b128 v[218:221], v211 offset:6144
	ds_read_b128 v[222:225], v211 offset:7168
	global_load_lds_dwordx4 v[238:239], off
	v_lshl_add_u64 v[238:239], v[114:115], 0, s[18:19]
	s_add_i32 m0, s35, 0xe000
	s_nop 0
	global_load_lds_dwordx4 v[238:239], off
	s_waitcnt vmcnt(24)
	s_waitcnt lgkmcnt(0)
	s_barrier
	s_setprio 1
	s_waitcnt lgkmcnt(0)
	v_mfma_f32_16x16x32_bf16 v[120:123], v[132:135], v[178:181], 0
	v_mfma_f32_16x16x32_bf16 v[116:119], v[140:143], v[178:181], 0
	v_mfma_f32_16x16x32_bf16 v[108:111], v[132:135], v[186:189], 0
	v_mfma_f32_16x16x32_bf16 v[104:107], v[140:143], v[186:189], 0
	v_mfma_f32_16x16x32_bf16 v[92:95], v[132:135], v[194:197], 0
	v_mfma_f32_16x16x32_bf16 v[88:91], v[140:143], v[194:197], 0
	v_mfma_f32_16x16x32_bf16 v[76:79], v[132:135], v[218:221], 0
	v_mfma_f32_16x16x32_bf16 v[72:75], v[140:143], v[218:221], 0
	v_mfma_f32_16x16x32_bf16 v[120:123], v[136:139], v[182:185], v[120:123]
	v_mfma_f32_16x16x32_bf16 v[116:119], v[144:147], v[182:185], v[116:119]
	v_mfma_f32_16x16x32_bf16 v[108:111], v[136:139], v[190:193], v[108:111]
	v_mfma_f32_16x16x32_bf16 v[104:107], v[144:147], v[190:193], v[104:107]
	v_mfma_f32_16x16x32_bf16 v[92:95], v[136:139], v[198:201], v[92:95]
	v_mfma_f32_16x16x32_bf16 v[88:91], v[144:147], v[198:201], v[88:91]
	v_mfma_f32_16x16x32_bf16 v[76:79], v[136:139], v[222:225], v[76:79]
	v_mfma_f32_16x16x32_bf16 v[72:75], v[144:147], v[222:225], v[72:75]
	s_setprio 0
	s_setprio 1
	v_mfma_f32_16x16x32_bf16 v[128:131], v[148:151], v[178:181], 0
	v_mfma_f32_16x16x32_bf16 v[124:127], v[170:173], v[178:181], 0
	v_mfma_f32_16x16x32_bf16 v[100:103], v[148:151], v[186:189], 0
	v_mfma_f32_16x16x32_bf16 v[96:99], v[170:173], v[186:189], 0
	v_mfma_f32_16x16x32_bf16 v[84:87], v[148:151], v[194:197], 0
	v_mfma_f32_16x16x32_bf16 v[80:83], v[170:173], v[194:197], 0
	v_mfma_f32_16x16x32_bf16 v[68:71], v[148:151], v[218:221], 0
	v_mfma_f32_16x16x32_bf16 v[64:67], v[170:173], v[218:221], 0
	v_mfma_f32_16x16x32_bf16 v[128:131], v[152:155], v[182:185], v[128:131]
	v_mfma_f32_16x16x32_bf16 v[124:127], v[174:177], v[182:185], v[124:127]
	v_mfma_f32_16x16x32_bf16 v[100:103], v[152:155], v[190:193], v[100:103]
	v_mfma_f32_16x16x32_bf16 v[96:99], v[174:177], v[190:193], v[96:99]
	v_mfma_f32_16x16x32_bf16 v[84:87], v[152:155], v[198:201], v[84:87]
	v_mfma_f32_16x16x32_bf16 v[80:83], v[174:177], v[198:201], v[80:83]
	v_mfma_f32_16x16x32_bf16 v[68:71], v[152:155], v[222:225], v[68:71]
	v_mfma_f32_16x16x32_bf16 v[64:67], v[174:177], v[222:225], v[64:67]
	s_setprio 0
	s_barrier
	s_add_i32 s68, s68, s31
	v_lshl_add_u64 v[238:239], s[24:25], 0, v[208:209]
	s_mov_b32 m0, s68
	ds_read_b128 v[178:181], v211 offset:16384
	ds_read_b128 v[182:185], v211 offset:17408
	ds_read_b128 v[186:189], v211 offset:18432
	ds_read_b128 v[190:193], v211 offset:19456
	ds_read_b128 v[194:197], v211 offset:20480
	ds_read_b128 v[198:201], v211 offset:21504
	ds_read_b128 v[218:221], v211 offset:22528
	ds_read_b128 v[222:225], v211 offset:23552
	global_load_lds_dwordx4 v[238:239], off
	s_add_i32 m0, s68, 0x2000
	s_add_u32 s68, s24, 0x40000
	v_lshl_add_u64 v[240:241], s[24:25], 0, v[156:157]
	s_addc_u32 s69, s25, 0
	s_add_i32 s70, s70, s31
	global_load_lds_dwordx4 v[240:241], off
	v_lshl_add_u64 v[242:243], s[68:69], 0, v[208:209]
	s_mov_b32 m0, s70
	s_nop 0
	global_load_lds_dwordx4 v[242:243], off
	v_lshl_add_u64 v[242:243], s[68:69], 0, v[156:157]
	s_add_i32 m0, s70, 0x2000
	s_nop 0
	global_load_lds_dwordx4 v[242:243], off
	v_lshl_add_u64 v[242:243], s[26:27], 0, v[160:161]
	s_mov_b32 m0, s35
	s_nop 0
	global_load_lds_dwordx4 v[242:243], off
	v_lshl_add_u64 v[242:243], s[26:27], 0, v[158:159]
	s_mov_b32 m0, s44
	s_nop 0
	global_load_lds_dwordx4 v[242:243], off
	s_waitcnt vmcnt(8)
	s_waitcnt lgkmcnt(0)
	s_barrier
; #define PG8_STAGE(bufoff, gbase, voff) do { _Pragma("unroll") for (int _i = 0; _i < 2; ++_i) \
;         __builtin_amdgcn_global_load_lds((const unsigned*)((const char*)(gbase) + (voff)[_i]), (PG8_LAS unsigned*)(lds + (bufoff) + ldsw + _i * 8192), 16, 0, 0); } while (0)
; #define PG8_LDA(dst, b, h) do { _Pragma("unroll") for (int m = 0; m < 4; ++m) _Pragma("unroll") for (int k = 0; k < 2; ++k) dst[m][k] = *(const PG8_LAS bf16x8*)(lds + PG8_SA(b, h) + aoff + m * 2048 + k * 1024); } while (0)
; #define PG8_LDB(dst, b, h) do { _Pragma("unroll") for (int n = 0; n < 2; ++n) _Pragma("unroll") for (int k = 0; k < 2; ++k) dst[n][k] = *(const PG8_LAS bf16x8*)(lds + PG8_SB(b, h) + boff + n * 2048 + k * 1024); } while (0)
; #define PG8_MMA(ai, bj, At, Bt) do { __builtin_amdgcn_s_setprio(1); _Pragma("unroll") for (int m = 0; m < 4; ++m) _Pragma("unroll") for (int n = 0; n < 2; ++n) _Pragma("unroll") for (int k = 0; k < 2; ++k) \
;         acc[ai][bj][m][n] = __builtin_amdgcn_mfma_f32_16x16x32_bf16(Bt[n][k], At[m][k], acc[ai][bj][m][n], 0, 0, 0); __builtin_amdgcn_s_setprio(0); } while (0)
; #define PG8_WAIT_V(n) asm volatile("s_waitcnt vmcnt(" #n ")" ::: "memory")
; #define PG8_WAIT_L(n) asm volatile("s_waitcnt lgkmcnt(" #n ")" ::: "memory")
; #define PG8_BAR __builtin_amdgcn_s_barrier()
; #define PG8_SCHED __builtin_amdgcn_sched_barrier(0)
;     ...
;             PG8_WAIT_V(8); PG8_WAIT_L(0); PG8_BAR; PG8_MMA(1, 0, At, B0); PG8_MMA(1, 1, At, B1); PG8_BAR; PG8_SCHED;
;             PG8_LDB(B0, 1, 0); PG8_LDB(B1, 1, 1); PG8_SCHED; PG8_LDA(At, 1, 0); PG8_STAGE(PG8_SA(0, 1), a2 + hstepA, voffA);
;             PG8_WAIT_V(8); PG8_WAIT_L(0); PG8_BAR; PG8_MMA(0, 0, At, B0); PG8_MMA(0, 1, At, B1); PG8_BAR; PG8_SCHED;
	s_setprio 1
	s_waitcnt lgkmcnt(0)
	v_mfma_f32_16x16x32_bf16 v[60:63], v[132:135], v[178:181], 0
	v_mfma_f32_16x16x32_bf16 v[56:59], v[140:143], v[178:181], 0
	v_mfma_f32_16x16x32_bf16 v[44:47], v[132:135], v[186:189], 0
	v_mfma_f32_16x16x32_bf16 v[40:43], v[140:143], v[186:189], 0
	v_mfma_f32_16x16x32_bf16 v[28:31], v[132:135], v[194:197], 0
	v_mfma_f32_16x16x32_bf16 v[24:27], v[140:143], v[194:197], 0
	v_mfma_f32_16x16x32_bf16 v[12:15], v[132:135], v[218:221], 0
	v_mfma_f32_16x16x32_bf16 v[8:11], v[140:143], v[218:221], 0
	v_mfma_f32_16x16x32_bf16 v[60:63], v[136:139], v[182:185], v[60:63]
	v_mfma_f32_16x16x32_bf16 v[56:59], v[144:147], v[182:185], v[56:59]
	v_mfma_f32_16x16x32_bf16 v[44:47], v[136:139], v[190:193], v[44:47]
	v_mfma_f32_16x16x32_bf16 v[40:43], v[144:147], v[190:193], v[40:43]
	v_mfma_f32_16x16x32_bf16 v[28:31], v[136:139], v[198:201], v[28:31]
	v_mfma_f32_16x16x32_bf16 v[24:27], v[144:147], v[198:201], v[24:27]
	v_mfma_f32_16x16x32_bf16 v[12:15], v[136:139], v[222:225], v[12:15]
	v_mfma_f32_16x16x32_bf16 v[8:11], v[144:147], v[222:225], v[8:11]
	s_setprio 0
	s_setprio 1
	v_mfma_f32_16x16x32_bf16 v[52:55], v[148:151], v[178:181], 0
	v_mfma_f32_16x16x32_bf16 v[48:51], v[170:173], v[178:181], 0
	v_mfma_f32_16x16x32_bf16 v[36:39], v[148:151], v[186:189], 0
	v_mfma_f32_16x16x32_bf16 v[32:35], v[170:173], v[186:189], 0
	v_mfma_f32_16x16x32_bf16 v[20:23], v[148:151], v[194:197], 0
	v_mfma_f32_16x16x32_bf16 v[16:19], v[170:173], v[194:197], 0
	v_mfma_f32_16x16x32_bf16 v[4:7], v[148:151], v[218:221], 0
	v_mfma_f32_16x16x32_bf16 v[0:3], v[170:173], v[218:221], 0
	v_mfma_f32_16x16x32_bf16 v[52:55], v[152:155], v[182:185], v[52:55]
	v_mfma_f32_16x16x32_bf16 v[48:51], v[174:177], v[182:185], v[48:51]
	v_mfma_f32_16x16x32_bf16 v[36:39], v[152:155], v[190:193], v[36:39]
	v_mfma_f32_16x16x32_bf16 v[32:35], v[174:177], v[190:193], v[32:35]
	v_mfma_f32_16x16x32_bf16 v[20:23], v[152:155], v[198:201], v[20:23]
	v_mfma_f32_16x16x32_bf16 v[16:19], v[174:177], v[198:201], v[16:19]
	v_mfma_f32_16x16x32_bf16 v[4:7], v[152:155], v[222:225], v[4:7]
	v_mfma_f32_16x16x32_bf16 v[0:3], v[174:177], v[222:225], v[0:3]
	s_setprio 0
	s_barrier
	s_add_i32 s68, 0, 0x18000
	s_add_i32 s69, 0, 0x1c000
	v_add_u32_e32 v144, s68, v203
	v_add_u32_e32 v174, s69, v203
	ds_read_b128 v[132:135], v144
	ds_read_b128 v[136:139], v144 offset:1024
	ds_read_b128 v[140:143], v144 offset:2048
	ds_read_b128 v[144:147], v144 offset:3072
	ds_read_b128 v[148:151], v174
	ds_read_b128 v[152:155], v174 offset:1024
	ds_read_b128 v[170:173], v174 offset:2048
	ds_read_b128 v[174:177], v174 offset:3072
	s_add_u32 s26, s26, 0x40000
	s_addc_u32 s27, s27, 0
	s_mov_b32 m0, s45
	v_lshl_add_u64 v[242:243], s[26:27], 0, v[160:161]
	ds_read_b128 v[178:181], v211 offset:32768
	ds_read_b128 v[182:185], v211 offset:33792
	ds_read_b128 v[186:189], v211 offset:34816
	ds_read_b128 v[190:193], v211 offset:35840
	ds_read_b128 v[194:197], v211 offset:36864
	ds_read_b128 v[198:201], v211 offset:37888
	ds_read_b128 v[218:221], v211 offset:38912
	ds_read_b128 v[222:225], v211 offset:39936
	global_load_lds_dwordx4 v[242:243], off
	v_lshl_add_u64 v[242:243], s[26:27], 0, v[158:159]
	s_mov_b32 m0, s46
	s_nop 0
	global_load_lds_dwordx4 v[242:243], off
	s_waitcnt vmcnt(8)
	s_waitcnt lgkmcnt(0)
	s_barrier
	s_setprio 1
	s_waitcnt lgkmcnt(0)
	v_mfma_f32_16x16x32_bf16 v[120:123], v[132:135], v[178:181], v[120:123]
	v_mfma_f32_16x16x32_bf16 v[116:119], v[140:143], v[178:181], v[116:119]
	v_mfma_f32_16x16x32_bf16 v[108:111], v[132:135], v[186:189], v[108:111]
	v_mfma_f32_16x16x32_bf16 v[104:107], v[140:143], v[186:189], v[104:107]
	v_mfma_f32_16x16x32_bf16 v[92:95], v[132:135], v[194:197], v[92:95]
	v_mfma_f32_16x16x32_bf16 v[88:91], v[140:143], v[194:197], v[88:91]
	v_mfma_f32_16x16x32_bf16 v[76:79], v[132:135], v[218:221], v[76:79]
	v_mfma_f32_16x16x32_bf16 v[72:75], v[140:143], v[218:221], v[72:75]
	v_mfma_f32_16x16x32_bf16 v[120:123], v[136:139], v[182:185], v[120:123]
	v_mfma_f32_16x16x32_bf16 v[116:119], v[144:147], v[182:185], v[116:119]
	v_mfma_f32_16x16x32_bf16 v[108:111], v[136:139], v[190:193], v[108:111]
	v_mfma_f32_16x16x32_bf16 v[104:107], v[144:147], v[190:193], v[104:107]
	v_mfma_f32_16x16x32_bf16 v[92:95], v[136:139], v[198:201], v[92:95]
	v_mfma_f32_16x16x32_bf16 v[88:91], v[144:147], v[198:201], v[88:91]
	v_mfma_f32_16x16x32_bf16 v[76:79], v[136:139], v[222:225], v[76:79]
	v_mfma_f32_16x16x32_bf16 v[72:75], v[144:147], v[222:225], v[72:75]
	s_setprio 0
	s_setprio 1
	v_mfma_f32_16x16x32_bf16 v[128:131], v[148:151], v[178:181], v[128:131]
	v_mfma_f32_16x16x32_bf16 v[124:127], v[170:173], v[178:181], v[124:127]
	v_mfma_f32_16x16x32_bf16 v[100:103], v[148:151], v[186:189], v[100:103]
	v_mfma_f32_16x16x32_bf16 v[96:99], v[170:173], v[186:189], v[96:99]
	v_mfma_f32_16x16x32_bf16 v[84:87], v[148:151], v[194:197], v[84:87]
	v_mfma_f32_16x16x32_bf16 v[80:83], v[170:173], v[194:197], v[80:83]
	v_mfma_f32_16x16x32_bf16 v[68:71], v[148:151], v[218:221], v[68:71]
	v_mfma_f32_16x16x32_bf16 v[64:67], v[170:173], v[218:221], v[64:67]
	v_mfma_f32_16x16x32_bf16 v[128:131], v[152:155], v[182:185], v[128:131]
	v_mfma_f32_16x16x32_bf16 v[124:127], v[174:177], v[182:185], v[124:127]
	v_mfma_f32_16x16x32_bf16 v[100:103], v[152:155], v[190:193], v[100:103]
	v_mfma_f32_16x16x32_bf16 v[96:99], v[174:177], v[190:193], v[96:99]
	v_mfma_f32_16x16x32_bf16 v[84:87], v[152:155], v[198:201], v[84:87]
	v_mfma_f32_16x16x32_bf16 v[80:83], v[174:177], v[198:201], v[80:83]
	v_mfma_f32_16x16x32_bf16 v[68:71], v[152:155], v[222:225], v[68:71]
	v_mfma_f32_16x16x32_bf16 v[64:67], v[174:177], v[222:225], v[64:67]
	s_setprio 0
	s_barrier
; #define PG8_STAGE(bufoff, gbase, voff) do { _Pragma("unroll") for (int _i = 0; _i < 2; ++_i) \
;         __builtin_amdgcn_global_load_lds((const unsigned*)((const char*)(gbase) + (voff)[_i]), (PG8_LAS unsigned*)(lds + (bufoff) + ldsw + _i * 8192), 16, 0, 0); } while (0)
; #define PG8_LDA(dst, b, h) do { _Pragma("unroll") for (int m = 0; m < 4; ++m) _Pragma("unroll") for (int k = 0; k < 2; ++k) dst[m][k] = *(const PG8_LAS bf16x8*)(lds + PG8_SA(b, h) + aoff + m * 2048 + k * 1024); } while (0)
; #define PG8_MMA(ai, bj, At, Bt) do { __builtin_amdgcn_s_setprio(1); _Pragma("unroll") for (int m = 0; m < 4; ++m) _Pragma("unroll") for (int n = 0; n < 2; ++n) _Pragma("unroll") for (int k = 0; k < 2; ++k) \
;         acc[ai][bj][m][n] = __builtin_amdgcn_mfma_f32_16x16x32_bf16(Bt[n][k], At[m][k], acc[ai][bj][m][n], 0, 0, 0); __builtin_amdgcn_s_setprio(0); } while (0)
; #define PG8_WAIT_V(n) asm volatile("s_waitcnt vmcnt(" #n ")" ::: "memory")
; #define PG8_WAIT_L(n) asm volatile("s_waitcnt lgkmcnt(" #n ")" ::: "memory")
; #define PG8_BAR __builtin_amdgcn_s_barrier()
; #define PG8_SCHED __builtin_amdgcn_sched_barrier(0)
;     ...
;             PG8_LDA(At, 1, 1); PG8_STAGE(PG8_SB(1, 0), b3, voffB); PG8_STAGE(PG8_SB(1, 1), b3 + hstepB, voffB); PG8_STAGE(PG8_SA(1, 0), a3, voffA);
;             PG8_WAIT_V(8); PG8_WAIT_L(0); PG8_BAR; PG8_MMA(1, 0, At, B0); PG8_MMA(1, 1, At, B1); PG8_BAR; PG8_SCHED;
;         }
	s_add_i32 s26, s68, s31
	v_lshl_add_u64 v[238:239], v[238:239], 0, s[72:73]
	s_mov_b32 m0, s26
	ds_read_b128 v[178:181], v211 offset:49152
	ds_read_b128 v[182:185], v211 offset:50176
	ds_read_b128 v[186:189], v211 offset:51200
	ds_read_b128 v[190:193], v211 offset:52224
	ds_read_b128 v[194:197], v211 offset:53248
	ds_read_b128 v[198:201], v211 offset:54272
	ds_read_b128 v[218:221], v211 offset:55296
	ds_read_b128 v[222:225], v211 offset:56320
	global_load_lds_dwordx4 v[238:239], off
	s_add_i32 m0, s26, 0x2000
	s_add_u32 s24, s24, 0x40080
	v_lshl_add_u64 v[238:239], v[240:241], 0, s[72:73]
	s_addc_u32 s25, s25, 0
	s_add_i32 s26, s69, s31
	global_load_lds_dwordx4 v[238:239], off
	v_lshl_add_u64 v[238:239], s[24:25], 0, v[208:209]
	s_mov_b32 m0, s26
	s_nop 0
	global_load_lds_dwordx4 v[238:239], off
	v_lshl_add_u64 v[238:239], s[24:25], 0, v[156:157]
	s_add_i32 m0, s26, 0x2000
	s_nop 0
	global_load_lds_dwordx4 v[238:239], off
	v_lshl_add_u64 v[238:239], s[20:21], 0, v[160:161]
	s_mov_b32 m0, s47
	s_nop 0
	global_load_lds_dwordx4 v[238:239], off
	v_lshl_add_u64 v[238:239], s[20:21], 0, v[158:159]
	s_mov_b32 m0, s48
	s_nop 0
	global_load_lds_dwordx4 v[238:239], off
	s_waitcnt vmcnt(8)
	s_waitcnt lgkmcnt(0)
	s_barrier
	s_setprio 1
	s_waitcnt lgkmcnt(0)
	v_mfma_f32_16x16x32_bf16 v[60:63], v[132:135], v[178:181], v[60:63]
	v_mfma_f32_16x16x32_bf16 v[56:59], v[140:143], v[178:181], v[56:59]
	v_mfma_f32_16x16x32_bf16 v[44:47], v[132:135], v[186:189], v[44:47]
	v_mfma_f32_16x16x32_bf16 v[40:43], v[140:143], v[186:189], v[40:43]
	v_mfma_f32_16x16x32_bf16 v[28:31], v[132:135], v[194:197], v[28:31]
	v_mfma_f32_16x16x32_bf16 v[24:27], v[140:143], v[194:197], v[24:27]
	v_mfma_f32_16x16x32_bf16 v[12:15], v[132:135], v[218:221], v[12:15]
	v_mfma_f32_16x16x32_bf16 v[8:11], v[140:143], v[218:221], v[8:11]
	v_mfma_f32_16x16x32_bf16 v[60:63], v[136:139], v[182:185], v[60:63]
	v_mfma_f32_16x16x32_bf16 v[56:59], v[144:147], v[182:185], v[56:59]
	v_mfma_f32_16x16x32_bf16 v[44:47], v[136:139], v[190:193], v[44:47]
	v_mfma_f32_16x16x32_bf16 v[40:43], v[144:147], v[190:193], v[40:43]
	v_mfma_f32_16x16x32_bf16 v[28:31], v[136:139], v[198:201], v[28:31]
	v_mfma_f32_16x16x32_bf16 v[24:27], v[144:147], v[198:201], v[24:27]
	v_mfma_f32_16x16x32_bf16 v[12:15], v[136:139], v[222:225], v[12:15]
	v_mfma_f32_16x16x32_bf16 v[8:11], v[144:147], v[222:225], v[8:11]
	s_setprio 0
	s_setprio 1
	v_mfma_f32_16x16x32_bf16 v[52:55], v[148:151], v[178:181], v[52:55]
	v_mfma_f32_16x16x32_bf16 v[48:51], v[170:173], v[178:181], v[48:51]
	v_mfma_f32_16x16x32_bf16 v[36:39], v[148:151], v[186:189], v[36:39]
	v_mfma_f32_16x16x32_bf16 v[32:35], v[170:173], v[186:189], v[32:35]
	v_mfma_f32_16x16x32_bf16 v[20:23], v[148:151], v[194:197], v[20:23]
	v_mfma_f32_16x16x32_bf16 v[16:19], v[170:173], v[194:197], v[16:19]
	v_mfma_f32_16x16x32_bf16 v[4:7], v[148:151], v[218:221], v[4:7]
	v_mfma_f32_16x16x32_bf16 v[0:3], v[170:173], v[218:221], v[0:3]
	v_mfma_f32_16x16x32_bf16 v[52:55], v[152:155], v[182:185], v[52:55]
	v_mfma_f32_16x16x32_bf16 v[48:51], v[174:177], v[182:185], v[48:51]
	v_mfma_f32_16x16x32_bf16 v[36:39], v[152:155], v[190:193], v[36:39]
	v_mfma_f32_16x16x32_bf16 v[32:35], v[174:177], v[190:193], v[32:35]
	v_mfma_f32_16x16x32_bf16 v[20:23], v[152:155], v[198:201], v[20:23]
	v_mfma_f32_16x16x32_bf16 v[16:19], v[174:177], v[198:201], v[16:19]
	v_mfma_f32_16x16x32_bf16 v[4:7], v[152:155], v[222:225], v[4:7]
	v_mfma_f32_16x16x32_bf16 v[0:3], v[174:177], v[222:225], v[0:3]
	s_setprio 0
	s_barrier
	s_add_i32 s67, s67, 2
	s_add_u32 s18, s18, 0x100
	s_addc_u32 s19, s19, 0
	s_cmp_gt_u32 s67, 13
	s_cbranch_scc0 .LBB0_451
	s_branch .Lpeel_exit_451

;     __device__ __forceinline__ const char* tile(const Unit& u, int t) const { return A + (size_t)u.pm * 2 * hstep() + (size_t)t * (BK * 2); }
;     __device__ __forceinline__ const char* tile(const Unit& u, int t) const { return U + (long)(t >> 2) * xoff + (size_t)u.pn * (1024 * 512) + (size_t)u.pm * 2 * hstep() + (size_t)(t & 3) * (BK * 2); }
; #define PG8_STAGE(bufoff, gbase, voff) do { _Pragma("unroll") for (int _i = 0; _i < 2; ++_i) \
;         __builtin_amdgcn_global_load_lds((const unsigned*)((const char*)(gbase) + (voff)[_i]), (PG8_LAS unsigned*)(lds + (bufoff) + ldsw + _i * 8192), 16, 0, 0); } while (0)
; #define PG8_LDA(dst, b, h) do { _Pragma("unroll") for (int m = 0; m < 4; ++m) _Pragma("unroll") for (int k = 0; k < 2; ++k) dst[m][k] = *(const PG8_LAS bf16x8*)(lds + PG8_SA(b, h) + aoff + m * 2048 + k * 1024); } while (0)
; #define PG8_LDB(dst, b, h) do { _Pragma("unroll") for (int n = 0; n < 2; ++n) _Pragma("unroll") for (int k = 0; k < 2; ++k) dst[n][k] = *(const PG8_LAS bf16x8*)(lds + PG8_SB(b, h) + boff + n * 2048 + k * 1024); } while (0)
; #define PG8_MMA(ai, bj, At, Bt) do { __builtin_amdgcn_s_setprio(1); _Pragma("unroll") for (int m = 0; m < 4; ++m) _Pragma("unroll") for (int n = 0; n < 2; ++n) _Pragma("unroll") for (int k = 0; k < 2; ++k) \
;         acc[ai][bj][m][n] = __builtin_amdgcn_mfma_f32_16x16x32_bf16(Bt[n][k], At[m][k], acc[ai][bj][m][n], 0, 0, 0); __builtin_amdgcn_s_setprio(0); } while (0)
; #define PG8_BAR __builtin_amdgcn_s_barrier()
;     ...
;         for (int t = 0; t < nt; t += 2) {
;             const bool last = (t == nt - 2);
;             const char* a1 = AS.tile(cur, t + 1);
;             const char* a2 = last ? AS.tile(nu, 0) : AS.tile(cur, t + 2); const char* b2 = last ? nB : cB + (size_t)(t + 2) * kstep;
;             const char* a3 = last ? AS.tile(nu, 1) : AS.tile(cur, t + 3); const char* b3 = b2 + kstep;
;             PG8_LDB(B0, 0, 0); PG8_LDB(B1, 0, 1); PG8_SCHED; PG8_LDA(At, 0, 0); PG8_STAGE(PG8_SA(1, 1), a1 + hstepA, voffA);
;             PG8_WAIT_V(8); PG8_WAIT_L(0); PG8_BAR; PG8_MMA(0, 0, At, B0); PG8_MMA(0, 1, At, B1); PG8_BAR; PG8_SCHED;
;             PG8_LDA(At, 0, 1); PG8_STAGE(PG8_SB(0, 0), b2, voffB); PG8_STAGE(PG8_SB(0, 1), b2 + hstepB, voffB); PG8_STAGE(PG8_SA(0, 0), a2, voffA);
;             PG8_WAIT_V(8); PG8_WAIT_L(0); PG8_BAR; PG8_MMA(1, 0, At, B0); PG8_MMA(1, 1, At, B1); PG8_BAR; PG8_SCHED;
.Lpeel_504:
	s_add_u32 s14, s52, s12
	s_addc_u32 s15, s53, s13
	s_add_u32 s18, s14, 0x400100
	s_addc_u32 s19, s15, 0
	s_add_u32 s16, s54, s12
	s_addc_u32 s17, s55, s13
	s_add_u32 s14, s14, 0x400180
	s_addc_u32 s15, s15, 0
	s_add_i32 s57, 0, 0x10000
	s_add_i32 s60, 0, 0x14000
	v_add_u32_e32 v146, s57, v149
	ds_read_b128 v[156:159], v146
	ds_read_b128 v[160:163], v146 offset:1024
	ds_read_b128 v[164:167], v146 offset:2048
	ds_read_b128 v[168:171], v146 offset:3072
	v_add_u32_e32 v146, s60, v149
	ds_read_b128 v[172:175], v146
	ds_read_b128 v[176:179], v146 offset:1024
	ds_read_b128 v[180:183], v146 offset:2048
	ds_read_b128 v[184:187], v146 offset:3072
	s_cmpk_eq_i32 s12, 0x700
	s_cselect_b32 s15, s51, s15
	s_cselect_b32 s14, s50, s14
	s_cselect_b32 s17, s48, s17
	s_cselect_b32 s16, s47, s16
	s_cselect_b32 s19, s49, s19
	s_cselect_b32 s18, s11, s18
	v_lshl_add_u64 v[146:147], v[142:143], 0, s[12:13]
	s_add_i32 m0, s26, 0xc000
	ds_read_b128 v[188:191], v152
	ds_read_b128 v[192:195], v152 offset:1024
	ds_read_b128 v[196:199], v152 offset:2048
	ds_read_b128 v[200:203], v152 offset:3072
	ds_read_b128 v[204:207], v152 offset:4096
	ds_read_b128 v[218:221], v152 offset:5120
	ds_read_b128 v[222:225], v152 offset:6144
	ds_read_b128 v[238:241], v152 offset:7168
	global_load_lds_dwordx4 v[146:147], off
	v_lshl_add_u64 v[146:147], v[144:145], 0, s[12:13]
	s_add_i32 m0, s26, 0xe000
	s_nop 0
	global_load_lds_dwordx4 v[146:147], off
	s_waitcnt vmcnt(24)
	s_waitcnt lgkmcnt(0)
	s_barrier
	s_setprio 1
	s_waitcnt lgkmcnt(0)
	v_mfma_f32_16x16x32_bf16 v[124:127], v[156:159], v[188:191], 0
	v_mfma_f32_16x16x32_bf16 v[120:123], v[164:167], v[188:191], 0
	v_mfma_f32_16x16x32_bf16 v[108:111], v[156:159], v[196:199], 0
	v_mfma_f32_16x16x32_bf16 v[104:107], v[164:167], v[196:199], 0
	v_mfma_f32_16x16x32_bf16 v[92:95], v[156:159], v[204:207], 0
	v_mfma_f32_16x16x32_bf16 v[88:91], v[164:167], v[204:207], 0
	v_mfma_f32_16x16x32_bf16 v[76:79], v[156:159], v[222:225], 0
	v_mfma_f32_16x16x32_bf16 v[72:75], v[164:167], v[222:225], 0
	v_mfma_f32_16x16x32_bf16 v[124:127], v[160:163], v[192:195], v[124:127]
	v_mfma_f32_16x16x32_bf16 v[120:123], v[168:171], v[192:195], v[120:123]
	v_mfma_f32_16x16x32_bf16 v[108:111], v[160:163], v[200:203], v[108:111]
	v_mfma_f32_16x16x32_bf16 v[104:107], v[168:171], v[200:203], v[104:107]
	v_mfma_f32_16x16x32_bf16 v[92:95], v[160:163], v[218:221], v[92:95]
	v_mfma_f32_16x16x32_bf16 v[88:91], v[168:171], v[218:221], v[88:91]
	v_mfma_f32_16x16x32_bf16 v[76:79], v[160:163], v[238:241], v[76:79]
	v_mfma_f32_16x16x32_bf16 v[72:75], v[168:171], v[238:241], v[72:75]
	s_setprio 0
	s_setprio 1
	v_mfma_f32_16x16x32_bf16 v[116:119], v[172:175], v[188:191], 0
	v_mfma_f32_16x16x32_bf16 v[112:115], v[180:183], v[188:191], 0
	v_mfma_f32_16x16x32_bf16 v[100:103], v[172:175], v[196:199], 0
	v_mfma_f32_16x16x32_bf16 v[96:99], v[180:183], v[196:199], 0
	v_mfma_f32_16x16x32_bf16 v[84:87], v[172:175], v[204:207], 0
	v_mfma_f32_16x16x32_bf16 v[80:83], v[180:183], v[204:207], 0
	v_mfma_f32_16x16x32_bf16 v[68:71], v[172:175], v[222:225], 0
	v_mfma_f32_16x16x32_bf16 v[64:67], v[180:183], v[222:225], 0
	v_mfma_f32_16x16x32_bf16 v[116:119], v[176:179], v[192:195], v[116:119]
	v_mfma_f32_16x16x32_bf16 v[112:115], v[184:187], v[192:195], v[112:115]
	v_mfma_f32_16x16x32_bf16 v[100:103], v[176:179], v[200:203], v[100:103]
	v_mfma_f32_16x16x32_bf16 v[96:99], v[184:187], v[200:203], v[96:99]
	v_mfma_f32_16x16x32_bf16 v[84:87], v[176:179], v[218:221], v[84:87]
	v_mfma_f32_16x16x32_bf16 v[80:83], v[184:187], v[218:221], v[80:83]
	v_mfma_f32_16x16x32_bf16 v[68:71], v[176:179], v[238:241], v[68:71]
	v_mfma_f32_16x16x32_bf16 v[64:67], v[184:187], v[238:241], v[64:67]
	s_setprio 0
	s_barrier
	s_add_i32 s57, s57, s25
	v_lshl_add_u64 v[146:147], s[16:17], 0, v[208:209]
	s_mov_b32 m0, s57
	ds_read_b128 v[188:191], v152 offset:16384
	ds_read_b128 v[192:195], v152 offset:17408
	ds_read_b128 v[196:199], v152 offset:18432
	ds_read_b128 v[200:203], v152 offset:19456
	ds_read_b128 v[204:207], v152 offset:20480
	ds_read_b128 v[218:221], v152 offset:21504
	ds_read_b128 v[222:225], v152 offset:22528
	ds_read_b128 v[238:241], v152 offset:23552
	global_load_lds_dwordx4 v[146:147], off
	s_add_i32 m0, s57, 0x2000
	s_add_u32 s58, s16, 0x40000
	v_lshl_add_u64 v[242:243], s[16:17], 0, v[128:129]
	s_addc_u32 s59, s17, 0
	s_add_i32 s57, s60, s25
	global_load_lds_dwordx4 v[242:243], off
	v_lshl_add_u64 v[244:245], s[58:59], 0, v[208:209]
	s_mov_b32 m0, s57
	s_nop 0
	global_load_lds_dwordx4 v[244:245], off
	v_lshl_add_u64 v[244:245], s[58:59], 0, v[128:129]
	s_add_i32 m0, s57, 0x2000
	s_nop 0
	global_load_lds_dwordx4 v[244:245], off
	v_lshl_add_u64 v[244:245], s[18:19], 0, v[132:133]
	s_mov_b32 m0, s26
	s_nop 0
	global_load_lds_dwordx4 v[244:245], off
	v_lshl_add_u64 v[244:245], s[18:19], 0, v[130:131]
	s_mov_b32 m0, s27
	s_nop 0
	global_load_lds_dwordx4 v[244:245], off
	s_waitcnt vmcnt(8)
	s_waitcnt lgkmcnt(0)
	s_barrier
; #define PG8_STAGE(bufoff, gbase, voff) do { _Pragma("unroll") for (int _i = 0; _i < 2; ++_i) \
;         __builtin_amdgcn_global_load_lds((const unsigned*)((const char*)(gbase) + (voff)[_i]), (PG8_LAS unsigned*)(lds + (bufoff) + ldsw + _i * 8192), 16, 0, 0); } while (0)
; #define PG8_LDA(dst, b, h) do { _Pragma("unroll") for (int m = 0; m < 4; ++m) _Pragma("unroll") for (int k = 0; k < 2; ++k) dst[m][k] = *(const PG8_LAS bf16x8*)(lds + PG8_SA(b, h) + aoff + m * 2048 + k * 1024); } while (0)
; #define PG8_LDB(dst, b, h) do { _Pragma("unroll") for (int n = 0; n < 2; ++n) _Pragma("unroll") for (int k = 0; k < 2; ++k) dst[n][k] = *(const PG8_LAS bf16x8*)(lds + PG8_SB(b, h) + boff + n * 2048 + k * 1024); } while (0)
; #define PG8_MMA(ai, bj, At, Bt) do { __builtin_amdgcn_s_setprio(1); _Pragma("unroll") for (int m = 0; m < 4; ++m) _Pragma("unroll") for (int n = 0; n < 2; ++n) _Pragma("unroll") for (int k = 0; k < 2; ++k) \
;         acc[ai][bj][m][n] = __builtin_amdgcn_mfma_f32_16x16x32_bf16(Bt[n][k], At[m][k], acc[ai][bj][m][n], 0, 0, 0); __builtin_amdgcn_s_setprio(0); } while (0)
; #define PG8_WAIT_V(n) asm volatile("s_waitcnt vmcnt(" #n ")" ::: "memory")
; #define PG8_WAIT_L(n) asm volatile("s_waitcnt lgkmcnt(" #n ")" ::: "memory")
; #define PG8_BAR __builtin_amdgcn_s_barrier()
; #define PG8_SCHED __builtin_amdgcn_sched_barrier(0)
;     ...
;             PG8_WAIT_V(8); PG8_WAIT_L(0); PG8_BAR; PG8_MMA(1, 0, At, B0); PG8_MMA(1, 1, At, B1); PG8_BAR; PG8_SCHED;
;             PG8_LDB(B0, 1, 0); PG8_LDB(B1, 1, 1); PG8_SCHED; PG8_LDA(At, 1, 0); PG8_STAGE(PG8_SA(0, 1), a2 + hstepA, voffA);
;             PG8_WAIT_V(8); PG8_WAIT_L(0); PG8_BAR; PG8_MMA(0, 0, At, B0); PG8_MMA(0, 1, At, B1); PG8_BAR; PG8_SCHED;
	s_setprio 1
	s_waitcnt lgkmcnt(0)
	v_mfma_f32_16x16x32_bf16 v[60:63], v[156:159], v[188:191], 0
	v_mfma_f32_16x16x32_bf16 v[56:59], v[164:167], v[188:191], 0
	v_mfma_f32_16x16x32_bf16 v[44:47], v[156:159], v[196:199], 0
	v_mfma_f32_16x16x32_bf16 v[40:43], v[164:167], v[196:199], 0
	v_mfma_f32_16x16x32_bf16 v[28:31], v[156:159], v[204:207], 0
	v_mfma_f32_16x16x32_bf16 v[24:27], v[164:167], v[204:207], 0
	v_mfma_f32_16x16x32_bf16 v[12:15], v[156:159], v[222:225], 0
	v_mfma_f32_16x16x32_bf16 v[8:11], v[164:167], v[222:225], 0
	v_mfma_f32_16x16x32_bf16 v[60:63], v[160:163], v[192:195], v[60:63]
	v_mfma_f32_16x16x32_bf16 v[56:59], v[168:171], v[192:195], v[56:59]
	v_mfma_f32_16x16x32_bf16 v[44:47], v[160:163], v[200:203], v[44:47]
	v_mfma_f32_16x16x32_bf16 v[40:43], v[168:171], v[200:203], v[40:43]
	v_mfma_f32_16x16x32_bf16 v[28:31], v[160:163], v[218:221], v[28:31]
	v_mfma_f32_16x16x32_bf16 v[24:27], v[168:171], v[218:221], v[24:27]
	v_mfma_f32_16x16x32_bf16 v[12:15], v[160:163], v[238:241], v[12:15]
	v_mfma_f32_16x16x32_bf16 v[8:11], v[168:171], v[238:241], v[8:11]
	s_setprio 0
	s_setprio 1
	v_mfma_f32_16x16x32_bf16 v[52:55], v[172:175], v[188:191], 0
	v_mfma_f32_16x16x32_bf16 v[48:51], v[180:183], v[188:191], 0
	v_mfma_f32_16x16x32_bf16 v[36:39], v[172:175], v[196:199], 0
	v_mfma_f32_16x16x32_bf16 v[32:35], v[180:183], v[196:199], 0
	v_mfma_f32_16x16x32_bf16 v[20:23], v[172:175], v[204:207], 0
	v_mfma_f32_16x16x32_bf16 v[16:19], v[180:183], v[204:207], 0
	v_mfma_f32_16x16x32_bf16 v[4:7], v[172:175], v[222:225], 0
	v_mfma_f32_16x16x32_bf16 v[0:3], v[180:183], v[222:225], 0
	v_mfma_f32_16x16x32_bf16 v[52:55], v[176:179], v[192:195], v[52:55]
	v_mfma_f32_16x16x32_bf16 v[48:51], v[184:187], v[192:195], v[48:51]
	v_mfma_f32_16x16x32_bf16 v[36:39], v[176:179], v[200:203], v[36:39]
	v_mfma_f32_16x16x32_bf16 v[32:35], v[184:187], v[200:203], v[32:35]
	v_mfma_f32_16x16x32_bf16 v[20:23], v[176:179], v[218:221], v[20:23]
	v_mfma_f32_16x16x32_bf16 v[16:19], v[184:187], v[218:221], v[16:19]
	v_mfma_f32_16x16x32_bf16 v[4:7], v[176:179], v[238:241], v[4:7]
	v_mfma_f32_16x16x32_bf16 v[0:3], v[184:187], v[238:241], v[0:3]
	s_setprio 0
	s_barrier
	s_add_i32 s57, 0, 0x18000
	v_add_u32_e32 v155, s57, v149
	s_add_i32 s58, 0, 0x1c000
	ds_read_b128 v[156:159], v155
	ds_read_b128 v[160:163], v155 offset:1024
	ds_read_b128 v[164:167], v155 offset:2048
	ds_read_b128 v[168:171], v155 offset:3072
	v_add_u32_e32 v155, s58, v149
	ds_read_b128 v[172:175], v155
	ds_read_b128 v[176:179], v155 offset:1024
	ds_read_b128 v[180:183], v155 offset:2048
	ds_read_b128 v[184:187], v155 offset:3072
	s_add_u32 s18, s18, 0x40000
	s_addc_u32 s19, s19, 0
	s_mov_b32 m0, s28
	v_lshl_add_u64 v[244:245], s[18:19], 0, v[132:133]
	ds_read_b128 v[188:191], v152 offset:32768
	ds_read_b128 v[192:195], v152 offset:33792
	ds_read_b128 v[196:199], v152 offset:34816
	ds_read_b128 v[200:203], v152 offset:35840
	ds_read_b128 v[204:207], v152 offset:36864
	ds_read_b128 v[218:221], v152 offset:37888
	ds_read_b128 v[222:225], v152 offset:38912
	ds_read_b128 v[238:241], v152 offset:39936
	global_load_lds_dwordx4 v[244:245], off
	v_lshl_add_u64 v[244:245], s[18:19], 0, v[130:131]
	s_mov_b32 m0, s29
	s_nop 0
	global_load_lds_dwordx4 v[244:245], off
	s_waitcnt vmcnt(8)
	s_waitcnt lgkmcnt(0)
	s_barrier
	s_setprio 1
	s_waitcnt lgkmcnt(0)
	v_mfma_f32_16x16x32_bf16 v[124:127], v[156:159], v[188:191], v[124:127]
	v_mfma_f32_16x16x32_bf16 v[120:123], v[164:167], v[188:191], v[120:123]
	v_mfma_f32_16x16x32_bf16 v[108:111], v[156:159], v[196:199], v[108:111]
	v_mfma_f32_16x16x32_bf16 v[104:107], v[164:167], v[196:199], v[104:107]
	v_mfma_f32_16x16x32_bf16 v[92:95], v[156:159], v[204:207], v[92:95]
	v_mfma_f32_16x16x32_bf16 v[88:91], v[164:167], v[204:207], v[88:91]
	v_mfma_f32_16x16x32_bf16 v[76:79], v[156:159], v[222:225], v[76:79]
	v_mfma_f32_16x16x32_bf16 v[72:75], v[164:167], v[222:225], v[72:75]
	v_mfma_f32_16x16x32_bf16 v[124:127], v[160:163], v[192:195], v[124:127]
	v_mfma_f32_16x16x32_bf16 v[120:123], v[168:171], v[192:195], v[120:123]
	v_mfma_f32_16x16x32_bf16 v[108:111], v[160:163], v[200:203], v[108:111]
	v_mfma_f32_16x16x32_bf16 v[104:107], v[168:171], v[200:203], v[104:107]
	v_mfma_f32_16x16x32_bf16 v[92:95], v[160:163], v[218:221], v[92:95]
	v_mfma_f32_16x16x32_bf16 v[88:91], v[168:171], v[218:221], v[88:91]
	v_mfma_f32_16x16x32_bf16 v[76:79], v[160:163], v[238:241], v[76:79]
	v_mfma_f32_16x16x32_bf16 v[72:75], v[168:171], v[238:241], v[72:75]
	s_setprio 0
	s_setprio 1
	v_mfma_f32_16x16x32_bf16 v[116:119], v[172:175], v[188:191], v[116:119]
	v_mfma_f32_16x16x32_bf16 v[112:115], v[180:183], v[188:191], v[112:115]
	v_mfma_f32_16x16x32_bf16 v[100:103], v[172:175], v[196:199], v[100:103]
	v_mfma_f32_16x16x32_bf16 v[96:99], v[180:183], v[196:199], v[96:99]
	v_mfma_f32_16x16x32_bf16 v[84:87], v[172:175], v[204:207], v[84:87]
	v_mfma_f32_16x16x32_bf16 v[80:83], v[180:183], v[204:207], v[80:83]
	v_mfma_f32_16x16x32_bf16 v[68:71], v[172:175], v[222:225], v[68:71]
	v_mfma_f32_16x16x32_bf16 v[64:67], v[180:183], v[222:225], v[64:67]
	v_mfma_f32_16x16x32_bf16 v[116:119], v[176:179], v[192:195], v[116:119]
	v_mfma_f32_16x16x32_bf16 v[112:115], v[184:187], v[192:195], v[112:115]
	v_mfma_f32_16x16x32_bf16 v[100:103], v[176:179], v[200:203], v[100:103]
	v_mfma_f32_16x16x32_bf16 v[96:99], v[184:187], v[200:203], v[96:99]
	v_mfma_f32_16x16x32_bf16 v[84:87], v[176:179], v[218:221], v[84:87]
	v_mfma_f32_16x16x32_bf16 v[80:83], v[184:187], v[218:221], v[80:83]
	v_mfma_f32_16x16x32_bf16 v[68:71], v[176:179], v[238:241], v[68:71]
	v_mfma_f32_16x16x32_bf16 v[64:67], v[184:187], v[238:241], v[64:67]
	s_setprio 0
	s_barrier
; #define PG8_STAGE(bufoff, gbase, voff) do { _Pragma("unroll") for (int _i = 0; _i < 2; ++_i) \
;         __builtin_amdgcn_global_load_lds((const unsigned*)((const char*)(gbase) + (voff)[_i]), (PG8_LAS unsigned*)(lds + (bufoff) + ldsw + _i * 8192), 16, 0, 0); } while (0)
; #define PG8_LDA(dst, b, h) do { _Pragma("unroll") for (int m = 0; m < 4; ++m) _Pragma("unroll") for (int k = 0; k < 2; ++k) dst[m][k] = *(const PG8_LAS bf16x8*)(lds + PG8_SA(b, h) + aoff + m * 2048 + k * 1024); } while (0)
; #define PG8_MMA(ai, bj, At, Bt) do { __builtin_amdgcn_s_setprio(1); _Pragma("unroll") for (int m = 0; m < 4; ++m) _Pragma("unroll") for (int n = 0; n < 2; ++n) _Pragma("unroll") for (int k = 0; k < 2; ++k) \
;         acc[ai][bj][m][n] = __builtin_amdgcn_mfma_f32_16x16x32_bf16(Bt[n][k], At[m][k], acc[ai][bj][m][n], 0, 0, 0); __builtin_amdgcn_s_setprio(0); } while (0)
; #define PG8_WAIT_V(n) asm volatile("s_waitcnt vmcnt(" #n ")" ::: "memory")
; #define PG8_WAIT_L(n) asm volatile("s_waitcnt lgkmcnt(" #n ")" ::: "memory")
; #define PG8_BAR __builtin_amdgcn_s_barrier()
; #define PG8_SCHED __builtin_amdgcn_sched_barrier(0)
;     ...
;             PG8_LDA(At, 1, 1); PG8_STAGE(PG8_SB(1, 0), b3, voffB); PG8_STAGE(PG8_SB(1, 1), b3 + hstepB, voffB); PG8_STAGE(PG8_SA(1, 0), a3, voffA);
;             PG8_WAIT_V(8); PG8_WAIT_L(0); PG8_BAR; PG8_MMA(1, 0, At, B0); PG8_MMA(1, 1, At, B1); PG8_BAR; PG8_SCHED;
;         }
	s_add_i32 s18, s57, s25
	v_lshl_add_u64 v[146:147], v[146:147], 0, s[64:65]
	s_mov_b32 m0, s18
	ds_read_b128 v[188:191], v152 offset:49152
	ds_read_b128 v[192:195], v152 offset:50176
	ds_read_b128 v[196:199], v152 offset:51200
	ds_read_b128 v[200:203], v152 offset:52224
	ds_read_b128 v[204:207], v152 offset:53248
	ds_read_b128 v[218:221], v152 offset:54272
	ds_read_b128 v[222:225], v152 offset:55296
	ds_read_b128 v[238:241], v152 offset:56320
	global_load_lds_dwordx4 v[146:147], off
	s_add_i32 m0, s18, 0x2000
	s_add_u32 s16, s16, 0x40080
	v_lshl_add_u64 v[146:147], v[242:243], 0, s[64:65]
	s_addc_u32 s17, s17, 0
	s_add_i32 s18, s58, s25
	global_load_lds_dwordx4 v[146:147], off
	v_lshl_add_u64 v[146:147], s[16:17], 0, v[208:209]
	s_mov_b32 m0, s18
	s_nop 0
	global_load_lds_dwordx4 v[146:147], off
	v_lshl_add_u64 v[146:147], s[16:17], 0, v[128:129]
	s_add_i32 m0, s18, 0x2000
	s_nop 0
	global_load_lds_dwordx4 v[146:147], off
	v_lshl_add_u64 v[146:147], s[14:15], 0, v[132:133]
	s_mov_b32 m0, s30
	s_nop 0
	global_load_lds_dwordx4 v[146:147], off
	v_lshl_add_u64 v[146:147], s[14:15], 0, v[130:131]
	s_mov_b32 m0, s31
	s_nop 0
	global_load_lds_dwordx4 v[146:147], off
	s_waitcnt vmcnt(8)
	s_waitcnt lgkmcnt(0)
	s_barrier
	s_setprio 1
	s_waitcnt lgkmcnt(0)
	v_mfma_f32_16x16x32_bf16 v[60:63], v[156:159], v[188:191], v[60:63]
	v_mfma_f32_16x16x32_bf16 v[56:59], v[164:167], v[188:191], v[56:59]
	v_mfma_f32_16x16x32_bf16 v[44:47], v[156:159], v[196:199], v[44:47]
	v_mfma_f32_16x16x32_bf16 v[40:43], v[164:167], v[196:199], v[40:43]
	v_mfma_f32_16x16x32_bf16 v[28:31], v[156:159], v[204:207], v[28:31]
	v_mfma_f32_16x16x32_bf16 v[24:27], v[164:167], v[204:207], v[24:27]
	v_mfma_f32_16x16x32_bf16 v[12:15], v[156:159], v[222:225], v[12:15]
	v_mfma_f32_16x16x32_bf16 v[8:11], v[164:167], v[222:225], v[8:11]
	v_mfma_f32_16x16x32_bf16 v[60:63], v[160:163], v[192:195], v[60:63]
	v_mfma_f32_16x16x32_bf16 v[56:59], v[168:171], v[192:195], v[56:59]
	v_mfma_f32_16x16x32_bf16 v[44:47], v[160:163], v[200:203], v[44:47]
	v_mfma_f32_16x16x32_bf16 v[40:43], v[168:171], v[200:203], v[40:43]
	v_mfma_f32_16x16x32_bf16 v[28:31], v[160:163], v[218:221], v[28:31]
	v_mfma_f32_16x16x32_bf16 v[24:27], v[168:171], v[218:221], v[24:27]
	v_mfma_f32_16x16x32_bf16 v[12:15], v[160:163], v[238:241], v[12:15]
	v_mfma_f32_16x16x32_bf16 v[8:11], v[168:171], v[238:241], v[8:11]
	s_setprio 0
	s_setprio 1
	v_mfma_f32_16x16x32_bf16 v[52:55], v[172:175], v[188:191], v[52:55]
	v_mfma_f32_16x16x32_bf16 v[48:51], v[180:183], v[188:191], v[48:51]
	v_mfma_f32_16x16x32_bf16 v[36:39], v[172:175], v[196:199], v[36:39]
	v_mfma_f32_16x16x32_bf16 v[32:35], v[180:183], v[196:199], v[32:35]
	v_mfma_f32_16x16x32_bf16 v[20:23], v[172:175], v[204:207], v[20:23]
	v_mfma_f32_16x16x32_bf16 v[16:19], v[180:183], v[204:207], v[16:19]
	v_mfma_f32_16x16x32_bf16 v[4:7], v[172:175], v[222:225], v[4:7]
	v_mfma_f32_16x16x32_bf16 v[0:3], v[180:183], v[222:225], v[0:3]
	v_mfma_f32_16x16x32_bf16 v[52:55], v[176:179], v[192:195], v[52:55]
	v_mfma_f32_16x16x32_bf16 v[48:51], v[184:187], v[192:195], v[48:51]
	v_mfma_f32_16x16x32_bf16 v[36:39], v[176:179], v[200:203], v[36:39]
	v_mfma_f32_16x16x32_bf16 v[32:35], v[184:187], v[200:203], v[32:35]
	v_mfma_f32_16x16x32_bf16 v[20:23], v[176:179], v[218:221], v[20:23]
	v_mfma_f32_16x16x32_bf16 v[16:19], v[184:187], v[218:221], v[16:19]
	v_mfma_f32_16x16x32_bf16 v[4:7], v[176:179], v[238:241], v[4:7]
	v_mfma_f32_16x16x32_bf16 v[0:3], v[184:187], v[238:241], v[0:3]
	s_setprio 0
	s_barrier
	s_add_i32 s56, s56, 2
	s_add_u32 s12, s12, 0x100
	s_addc_u32 s13, s13, 0
	s_cmp_gt_u32 s56, 13
	s_cbranch_scc0 .LBB0_504
	s_branch .Lpeel_exit_504

;     __device__ __forceinline__ const char* tile(const Unit& u, int t) const { return A + (size_t)u.pm * 2 * hstep() + (size_t)t * (BK * 2); }
;     __device__ __forceinline__ const char* tile(const Unit& u, int t) const { return U + (long)(t >> 2) * xoff + (size_t)u.pn * (1024 * 512) + (size_t)u.pm * 2 * hstep() + (size_t)(t & 3) * (BK * 2); }
; #define PG8_STAGE(bufoff, gbase, voff) do { _Pragma("unroll") for (int _i = 0; _i < 2; ++_i) \
;         __builtin_amdgcn_global_load_lds((const unsigned*)((const char*)(gbase) + (voff)[_i]), (PG8_LAS unsigned*)(lds + (bufoff) + ldsw + _i * 8192), 16, 0, 0); } while (0)
; #define PG8_LDA(dst, b, h) do { _Pragma("unroll") for (int m = 0; m < 4; ++m) _Pragma("unroll") for (int k = 0; k < 2; ++k) dst[m][k] = *(const PG8_LAS bf16x8*)(lds + PG8_SA(b, h) + aoff + m * 2048 + k * 1024); } while (0)
; #define PG8_LDB(dst, b, h) do { _Pragma("unroll") for (int n = 0; n < 2; ++n) _Pragma("unroll") for (int k = 0; k < 2; ++k) dst[n][k] = *(const PG8_LAS bf16x8*)(lds + PG8_SB(b, h) + boff + n * 2048 + k * 1024); } while (0)
; #define PG8_MMA(ai, bj, At, Bt) do { __builtin_amdgcn_s_setprio(1); _Pragma("unroll") for (int m = 0; m < 4; ++m) _Pragma("unroll") for (int n = 0; n < 2; ++n) _Pragma("unroll") for (int k = 0; k < 2; ++k) \
;         acc[ai][bj][m][n] = __builtin_amdgcn_mfma_f32_16x16x32_bf16(Bt[n][k], At[m][k], acc[ai][bj][m][n], 0, 0, 0); __builtin_amdgcn_s_setprio(0); } while (0)
; #define PG8_BAR __builtin_amdgcn_s_barrier()
;     ...
;         for (int t = 0; t < nt; t += 2) {
;             const bool last = (t == nt - 2);
;             const char* a1 = AS.tile(cur, t + 1);
;             const char* a2 = last ? AS.tile(nu, 0) : AS.tile(cur, t + 2); const char* b2 = last ? nB : cB + (size_t)(t + 2) * kstep;
;             const char* a3 = last ? AS.tile(nu, 1) : AS.tile(cur, t + 3); const char* b3 = b2 + kstep;
;             PG8_LDB(B0, 0, 0); PG8_LDB(B1, 0, 1); PG8_SCHED; PG8_LDA(At, 0, 0); PG8_STAGE(PG8_SA(1, 1), a1 + hstepA, voffA);
;             PG8_WAIT_V(8); PG8_WAIT_L(0); PG8_BAR; PG8_MMA(0, 0, At, B0); PG8_MMA(0, 1, At, B1); PG8_BAR; PG8_SCHED;
;             PG8_LDA(At, 0, 1); PG8_STAGE(PG8_SB(0, 0), b2, voffB); PG8_STAGE(PG8_SB(0, 1), b2 + hstepB, voffB); PG8_STAGE(PG8_SA(0, 0), a2, voffA);
;             PG8_WAIT_V(8); PG8_WAIT_L(0); PG8_BAR; PG8_MMA(1, 0, At, B0); PG8_MMA(1, 1, At, B1); PG8_BAR; PG8_SCHED;
.Lpeel_702:
	s_add_u32 s20, s40, s2
	s_addc_u32 s21, s41, s3
	s_add_u32 s26, s20, 0x400100
	s_addc_u32 s27, s21, 0
	s_add_u32 s24, s42, s2
	s_addc_u32 s25, s43, s3
	s_add_u32 s20, s20, 0x400180
	s_addc_u32 s21, s21, 0
	s_add_i32 s63, 0, 0x10000
	s_add_i32 s66, 0, 0x14000
	v_add_u32_e32 v156, s63, v185
	v_add_u32_e32 v172, s66, v185
	ds_read_b128 v[132:135], v156
	ds_read_b128 v[136:139], v156 offset:1024
	ds_read_b128 v[140:143], v156 offset:2048
	ds_read_b128 v[156:159], v156 offset:3072
	ds_read_b128 v[160:163], v172
	ds_read_b128 v[164:167], v172 offset:1024
	ds_read_b128 v[168:171], v172 offset:2048
	ds_read_b128 v[172:175], v172 offset:3072
	s_cmpk_eq_i32 s2, 0x700
	s_cselect_b32 s21, s31, s21
	s_cselect_b32 s20, s30, s20
	s_cselect_b32 s25, s28, s25
	s_cselect_b32 s24, s1, s24
	s_cselect_b32 s27, s29, s27
	s_cselect_b32 s26, s19, s26
	v_lshl_add_u64 v[238:239], v[128:129], 0, s[2:3]
	s_add_i32 m0, s49, 0xc000
	ds_read_b128 v[176:179], v190
	ds_read_b128 v[180:183], v190 offset:1024
	ds_read_b128 v[192:195], v190 offset:2048
	ds_read_b128 v[196:199], v190 offset:3072
	ds_read_b128 v[200:203], v190 offset:4096
	ds_read_b128 v[204:207], v190 offset:5120
	ds_read_b128 v[218:221], v190 offset:6144
	ds_read_b128 v[222:225], v190 offset:7168
	global_load_lds_dwordx4 v[238:239], off
	v_lshl_add_u64 v[238:239], v[130:131], 0, s[2:3]
	s_add_i32 m0, s49, 0xe000
	s_nop 0
	global_load_lds_dwordx4 v[238:239], off
	s_waitcnt vmcnt(24)
	s_waitcnt lgkmcnt(0)
	s_barrier
	s_setprio 1
	s_waitcnt lgkmcnt(0)
	v_mfma_f32_16x16x32_bf16 v[124:127], v[132:135], v[176:179], 0
	v_mfma_f32_16x16x32_bf16 v[120:123], v[140:143], v[176:179], 0
	v_mfma_f32_16x16x32_bf16 v[112:115], v[132:135], v[192:195], 0
	v_mfma_f32_16x16x32_bf16 v[104:107], v[140:143], v[192:195], 0
	v_mfma_f32_16x16x32_bf16 v[96:99], v[132:135], v[200:203], 0
	v_mfma_f32_16x16x32_bf16 v[88:91], v[140:143], v[200:203], 0
	v_mfma_f32_16x16x32_bf16 v[80:83], v[132:135], v[218:221], 0
	v_mfma_f32_16x16x32_bf16 v[72:75], v[140:143], v[218:221], 0
	v_mfma_f32_16x16x32_bf16 v[124:127], v[136:139], v[180:183], v[124:127]
	v_mfma_f32_16x16x32_bf16 v[120:123], v[156:159], v[180:183], v[120:123]
	v_mfma_f32_16x16x32_bf16 v[112:115], v[136:139], v[196:199], v[112:115]
	v_mfma_f32_16x16x32_bf16 v[104:107], v[156:159], v[196:199], v[104:107]
	v_mfma_f32_16x16x32_bf16 v[96:99], v[136:139], v[204:207], v[96:99]
	v_mfma_f32_16x16x32_bf16 v[88:91], v[156:159], v[204:207], v[88:91]
	v_mfma_f32_16x16x32_bf16 v[80:83], v[136:139], v[222:225], v[80:83]
	v_mfma_f32_16x16x32_bf16 v[72:75], v[156:159], v[222:225], v[72:75]
	s_setprio 0
	s_setprio 1
	v_mfma_f32_16x16x32_bf16 v[116:119], v[160:163], v[176:179], 0
	v_mfma_f32_16x16x32_bf16 v[108:111], v[168:171], v[176:179], 0
	v_mfma_f32_16x16x32_bf16 v[100:103], v[160:163], v[192:195], 0
	v_mfma_f32_16x16x32_bf16 v[92:95], v[168:171], v[192:195], 0
	v_mfma_f32_16x16x32_bf16 v[84:87], v[160:163], v[200:203], 0
	v_mfma_f32_16x16x32_bf16 v[76:79], v[168:171], v[200:203], 0
	v_mfma_f32_16x16x32_bf16 v[68:71], v[160:163], v[218:221], 0
	v_mfma_f32_16x16x32_bf16 v[64:67], v[168:171], v[218:221], 0
	v_mfma_f32_16x16x32_bf16 v[116:119], v[164:167], v[180:183], v[116:119]
	v_mfma_f32_16x16x32_bf16 v[108:111], v[172:175], v[180:183], v[108:111]
	v_mfma_f32_16x16x32_bf16 v[100:103], v[164:167], v[196:199], v[100:103]
	v_mfma_f32_16x16x32_bf16 v[92:95], v[172:175], v[196:199], v[92:95]
	v_mfma_f32_16x16x32_bf16 v[84:87], v[164:167], v[204:207], v[84:87]
	v_mfma_f32_16x16x32_bf16 v[76:79], v[172:175], v[204:207], v[76:79]
	v_mfma_f32_16x16x32_bf16 v[68:71], v[164:167], v[222:225], v[68:71]
	v_mfma_f32_16x16x32_bf16 v[64:67], v[172:175], v[222:225], v[64:67]
	s_setprio 0
	s_barrier
	s_add_i32 s63, s63, s48
	v_lshl_add_u64 v[238:239], s[24:25], 0, v[148:149]
	s_mov_b32 m0, s63
	ds_read_b128 v[176:179], v190 offset:16384
	ds_read_b128 v[180:183], v190 offset:17408
	ds_read_b128 v[192:195], v190 offset:18432
	ds_read_b128 v[196:199], v190 offset:19456
	ds_read_b128 v[200:203], v190 offset:20480
	ds_read_b128 v[204:207], v190 offset:21504
	ds_read_b128 v[218:221], v190 offset:22528
	ds_read_b128 v[222:225], v190 offset:23552
	global_load_lds_dwordx4 v[238:239], off
	s_add_i32 m0, s63, 0x2000
	s_add_u32 s64, s24, 0x40000
	v_lshl_add_u64 v[240:241], s[24:25], 0, v[144:145]
	s_addc_u32 s65, s25, 0
	s_add_i32 s63, s66, s48
	global_load_lds_dwordx4 v[240:241], off
	v_lshl_add_u64 v[242:243], s[64:65], 0, v[148:149]
	s_mov_b32 m0, s63
	s_nop 0
	global_load_lds_dwordx4 v[242:243], off
	v_lshl_add_u64 v[242:243], s[64:65], 0, v[144:145]
	s_add_i32 m0, s63, 0x2000
	s_nop 0
	global_load_lds_dwordx4 v[242:243], off
	v_lshl_add_u64 v[242:243], s[26:27], 0, v[150:151]
	s_mov_b32 m0, s49
	s_nop 0
	global_load_lds_dwordx4 v[242:243], off
	v_lshl_add_u64 v[242:243], s[26:27], 0, v[146:147]
	s_mov_b32 m0, s50
	s_nop 0
	global_load_lds_dwordx4 v[242:243], off
	s_waitcnt vmcnt(8)
	s_waitcnt lgkmcnt(0)
	s_barrier
; #define PG8_STAGE(bufoff, gbase, voff) do { _Pragma("unroll") for (int _i = 0; _i < 2; ++_i) \
;         __builtin_amdgcn_global_load_lds((const unsigned*)((const char*)(gbase) + (voff)[_i]), (PG8_LAS unsigned*)(lds + (bufoff) + ldsw + _i * 8192), 16, 0, 0); } while (0)
; #define PG8_LDA(dst, b, h) do { _Pragma("unroll") for (int m = 0; m < 4; ++m) _Pragma("unroll") for (int k = 0; k < 2; ++k) dst[m][k] = *(const PG8_LAS bf16x8*)(lds + PG8_SA(b, h) + aoff + m * 2048 + k * 1024); } while (0)
; #define PG8_LDB(dst, b, h) do { _Pragma("unroll") for (int n = 0; n < 2; ++n) _Pragma("unroll") for (int k = 0; k < 2; ++k) dst[n][k] = *(const PG8_LAS bf16x8*)(lds + PG8_SB(b, h) + boff + n * 2048 + k * 1024); } while (0)
; #define PG8_MMA(ai, bj, At, Bt) do { __builtin_amdgcn_s_setprio(1); _Pragma("unroll") for (int m = 0; m < 4; ++m) _Pragma("unroll") for (int n = 0; n < 2; ++n) _Pragma("unroll") for (int k = 0; k < 2; ++k) \
;         acc[ai][bj][m][n] = __builtin_amdgcn_mfma_f32_16x16x32_bf16(Bt[n][k], At[m][k], acc[ai][bj][m][n], 0, 0, 0); __builtin_amdgcn_s_setprio(0); } while (0)
; #define PG8_WAIT_V(n) asm volatile("s_waitcnt vmcnt(" #n ")" ::: "memory")
; #define PG8_WAIT_L(n) asm volatile("s_waitcnt lgkmcnt(" #n ")" ::: "memory")
; #define PG8_BAR __builtin_amdgcn_s_barrier()
; #define PG8_SCHED __builtin_amdgcn_sched_barrier(0)
;     ...
;             PG8_WAIT_V(8); PG8_WAIT_L(0); PG8_BAR; PG8_MMA(1, 0, At, B0); PG8_MMA(1, 1, At, B1); PG8_BAR; PG8_SCHED;
;             PG8_LDB(B0, 1, 0); PG8_LDB(B1, 1, 1); PG8_SCHED; PG8_LDA(At, 1, 0); PG8_STAGE(PG8_SA(0, 1), a2 + hstepA, voffA);
;             PG8_WAIT_V(8); PG8_WAIT_L(0); PG8_BAR; PG8_MMA(0, 0, At, B0); PG8_MMA(0, 1, At, B1); PG8_BAR; PG8_SCHED;
	s_setprio 1
	s_waitcnt lgkmcnt(0)
	v_mfma_f32_16x16x32_bf16 v[60:63], v[132:135], v[176:179], 0
	v_mfma_f32_16x16x32_bf16 v[56:59], v[140:143], v[176:179], 0
	v_mfma_f32_16x16x32_bf16 v[48:51], v[132:135], v[192:195], 0
	v_mfma_f32_16x16x32_bf16 v[40:43], v[140:143], v[192:195], 0
	v_mfma_f32_16x16x32_bf16 v[32:35], v[132:135], v[200:203], 0
	v_mfma_f32_16x16x32_bf16 v[24:27], v[140:143], v[200:203], 0
	v_mfma_f32_16x16x32_bf16 v[16:19], v[132:135], v[218:221], 0
	v_mfma_f32_16x16x32_bf16 v[8:11], v[140:143], v[218:221], 0
	v_mfma_f32_16x16x32_bf16 v[60:63], v[136:139], v[180:183], v[60:63]
	v_mfma_f32_16x16x32_bf16 v[56:59], v[156:159], v[180:183], v[56:59]
	v_mfma_f32_16x16x32_bf16 v[48:51], v[136:139], v[196:199], v[48:51]
	v_mfma_f32_16x16x32_bf16 v[40:43], v[156:159], v[196:199], v[40:43]
	v_mfma_f32_16x16x32_bf16 v[32:35], v[136:139], v[204:207], v[32:35]
	v_mfma_f32_16x16x32_bf16 v[24:27], v[156:159], v[204:207], v[24:27]
	v_mfma_f32_16x16x32_bf16 v[16:19], v[136:139], v[222:225], v[16:19]
	v_mfma_f32_16x16x32_bf16 v[8:11], v[156:159], v[222:225], v[8:11]
	s_setprio 0
	s_setprio 1
	v_mfma_f32_16x16x32_bf16 v[52:55], v[160:163], v[176:179], 0
	v_mfma_f32_16x16x32_bf16 v[44:47], v[168:171], v[176:179], 0
	v_mfma_f32_16x16x32_bf16 v[36:39], v[160:163], v[192:195], 0
	v_mfma_f32_16x16x32_bf16 v[28:31], v[168:171], v[192:195], 0
	v_mfma_f32_16x16x32_bf16 v[20:23], v[160:163], v[200:203], 0
	v_mfma_f32_16x16x32_bf16 v[12:15], v[168:171], v[200:203], 0
	v_mfma_f32_16x16x32_bf16 v[4:7], v[160:163], v[218:221], 0
	v_mfma_f32_16x16x32_bf16 v[0:3], v[168:171], v[218:221], 0
	v_mfma_f32_16x16x32_bf16 v[52:55], v[164:167], v[180:183], v[52:55]
	v_mfma_f32_16x16x32_bf16 v[44:47], v[172:175], v[180:183], v[44:47]
	v_mfma_f32_16x16x32_bf16 v[36:39], v[164:167], v[196:199], v[36:39]
	v_mfma_f32_16x16x32_bf16 v[28:31], v[172:175], v[196:199], v[28:31]
	v_mfma_f32_16x16x32_bf16 v[20:23], v[164:167], v[204:207], v[20:23]
	v_mfma_f32_16x16x32_bf16 v[12:15], v[172:175], v[204:207], v[12:15]
	v_mfma_f32_16x16x32_bf16 v[4:7], v[164:167], v[222:225], v[4:7]
	v_mfma_f32_16x16x32_bf16 v[0:3], v[172:175], v[222:225], v[0:3]
	s_setprio 0
	s_barrier
	s_add_i32 s63, 0, 0x18000
	s_add_i32 s64, 0, 0x1c000
	v_add_u32_e32 v156, s63, v185
	v_add_u32_e32 v172, s64, v185
	ds_read_b128 v[132:135], v156
	ds_read_b128 v[136:139], v156 offset:1024
	ds_read_b128 v[140:143], v156 offset:2048
	ds_read_b128 v[156:159], v156 offset:3072
	ds_read_b128 v[160:163], v172
	ds_read_b128 v[164:167], v172 offset:1024
	ds_read_b128 v[168:171], v172 offset:2048
	ds_read_b128 v[172:175], v172 offset:3072
	s_add_u32 s26, s26, 0x40000
	s_addc_u32 s27, s27, 0
	s_mov_b32 m0, s51
	v_lshl_add_u64 v[242:243], s[26:27], 0, v[150:151]
	ds_read_b128 v[176:179], v190 offset:32768
	ds_read_b128 v[180:183], v190 offset:33792
	ds_read_b128 v[192:195], v190 offset:34816
	ds_read_b128 v[196:199], v190 offset:35840
	ds_read_b128 v[200:203], v190 offset:36864
	ds_read_b128 v[204:207], v190 offset:37888
	ds_read_b128 v[218:221], v190 offset:38912
	ds_read_b128 v[222:225], v190 offset:39936
	global_load_lds_dwordx4 v[242:243], off
	v_lshl_add_u64 v[242:243], s[26:27], 0, v[146:147]
	s_mov_b32 m0, s52
	s_nop 0
	global_load_lds_dwordx4 v[242:243], off
	s_waitcnt vmcnt(8)
	s_waitcnt lgkmcnt(0)
	s_barrier
	s_setprio 1
	s_waitcnt lgkmcnt(0)
	v_mfma_f32_16x16x32_bf16 v[124:127], v[132:135], v[176:179], v[124:127]
	v_mfma_f32_16x16x32_bf16 v[120:123], v[140:143], v[176:179], v[120:123]
	v_mfma_f32_16x16x32_bf16 v[112:115], v[132:135], v[192:195], v[112:115]
	v_mfma_f32_16x16x32_bf16 v[104:107], v[140:143], v[192:195], v[104:107]
	v_mfma_f32_16x16x32_bf16 v[96:99], v[132:135], v[200:203], v[96:99]
	v_mfma_f32_16x16x32_bf16 v[88:91], v[140:143], v[200:203], v[88:91]
	v_mfma_f32_16x16x32_bf16 v[80:83], v[132:135], v[218:221], v[80:83]
	v_mfma_f32_16x16x32_bf16 v[72:75], v[140:143], v[218:221], v[72:75]
	v_mfma_f32_16x16x32_bf16 v[124:127], v[136:139], v[180:183], v[124:127]
	v_mfma_f32_16x16x32_bf16 v[120:123], v[156:159], v[180:183], v[120:123]
	v_mfma_f32_16x16x32_bf16 v[112:115], v[136:139], v[196:199], v[112:115]
	v_mfma_f32_16x16x32_bf16 v[104:107], v[156:159], v[196:199], v[104:107]
	v_mfma_f32_16x16x32_bf16 v[96:99], v[136:139], v[204:207], v[96:99]
	v_mfma_f32_16x16x32_bf16 v[88:91], v[156:159], v[204:207], v[88:91]
	v_mfma_f32_16x16x32_bf16 v[80:83], v[136:139], v[222:225], v[80:83]
	v_mfma_f32_16x16x32_bf16 v[72:75], v[156:159], v[222:225], v[72:75]
	s_setprio 0
	s_setprio 1
	v_mfma_f32_16x16x32_bf16 v[116:119], v[160:163], v[176:179], v[116:119]
	v_mfma_f32_16x16x32_bf16 v[108:111], v[168:171], v[176:179], v[108:111]
	v_mfma_f32_16x16x32_bf16 v[100:103], v[160:163], v[192:195], v[100:103]
	v_mfma_f32_16x16x32_bf16 v[92:95], v[168:171], v[192:195], v[92:95]
	v_mfma_f32_16x16x32_bf16 v[84:87], v[160:163], v[200:203], v[84:87]
	v_mfma_f32_16x16x32_bf16 v[76:79], v[168:171], v[200:203], v[76:79]
	v_mfma_f32_16x16x32_bf16 v[68:71], v[160:163], v[218:221], v[68:71]
	v_mfma_f32_16x16x32_bf16 v[64:67], v[168:171], v[218:221], v[64:67]
	v_mfma_f32_16x16x32_bf16 v[116:119], v[164:167], v[180:183], v[116:119]
	v_mfma_f32_16x16x32_bf16 v[108:111], v[172:175], v[180:183], v[108:111]
	v_mfma_f32_16x16x32_bf16 v[100:103], v[164:167], v[196:199], v[100:103]
	v_mfma_f32_16x16x32_bf16 v[92:95], v[172:175], v[196:199], v[92:95]
	v_mfma_f32_16x16x32_bf16 v[84:87], v[164:167], v[204:207], v[84:87]
	v_mfma_f32_16x16x32_bf16 v[76:79], v[172:175], v[204:207], v[76:79]
	v_mfma_f32_16x16x32_bf16 v[68:71], v[164:167], v[222:225], v[68:71]
	v_mfma_f32_16x16x32_bf16 v[64:67], v[172:175], v[222:225], v[64:67]
	s_setprio 0
	s_barrier
; #define PG8_STAGE(bufoff, gbase, voff) do { _Pragma("unroll") for (int _i = 0; _i < 2; ++_i) \
;         __builtin_amdgcn_global_load_lds((const unsigned*)((const char*)(gbase) + (voff)[_i]), (PG8_LAS unsigned*)(lds + (bufoff) + ldsw + _i * 8192), 16, 0, 0); } while (0)
; #define PG8_LDA(dst, b, h) do { _Pragma("unroll") for (int m = 0; m < 4; ++m) _Pragma("unroll") for (int k = 0; k < 2; ++k) dst[m][k] = *(const PG8_LAS bf16x8*)(lds + PG8_SA(b, h) + aoff + m * 2048 + k * 1024); } while (0)
; #define PG8_MMA(ai, bj, At, Bt) do { __builtin_amdgcn_s_setprio(1); _Pragma("unroll") for (int m = 0; m < 4; ++m) _Pragma("unroll") for (int n = 0; n < 2; ++n) _Pragma("unroll") for (int k = 0; k < 2; ++k) \
;         acc[ai][bj][m][n] = __builtin_amdgcn_mfma_f32_16x16x32_bf16(Bt[n][k], At[m][k], acc[ai][bj][m][n], 0, 0, 0); __builtin_amdgcn_s_setprio(0); } while (0)
; #define PG8_WAIT_V(n) asm volatile("s_waitcnt vmcnt(" #n ")" ::: "memory")
; #define PG8_WAIT_L(n) asm volatile("s_waitcnt lgkmcnt(" #n ")" ::: "memory")
; #define PG8_BAR __builtin_amdgcn_s_barrier()
; #define PG8_SCHED __builtin_amdgcn_sched_barrier(0)
;     ...
;             PG8_LDA(At, 1, 1); PG8_STAGE(PG8_SB(1, 0), b3, voffB); PG8_STAGE(PG8_SB(1, 1), b3 + hstepB, voffB); PG8_STAGE(PG8_SA(1, 0), a3, voffA);
;             PG8_WAIT_V(8); PG8_WAIT_L(0); PG8_BAR; PG8_MMA(1, 0, At, B0); PG8_MMA(1, 1, At, B1); PG8_BAR; PG8_SCHED;
;         }
	s_add_i32 s26, s63, s48
	v_lshl_add_u64 v[238:239], v[238:239], 0, s[68:69]
	s_mov_b32 m0, s26
	ds_read_b128 v[176:179], v190 offset:49152
	ds_read_b128 v[180:183], v190 offset:50176
	ds_read_b128 v[192:195], v190 offset:51200
	ds_read_b128 v[196:199], v190 offset:52224
	ds_read_b128 v[200:203], v190 offset:53248
	ds_read_b128 v[204:207], v190 offset:54272
	ds_read_b128 v[218:221], v190 offset:55296
	ds_read_b128 v[222:225], v190 offset:56320
	global_load_lds_dwordx4 v[238:239], off
	s_add_i32 m0, s26, 0x2000
	s_add_u32 s24, s24, 0x40080
	v_lshl_add_u64 v[238:239], v[240:241], 0, s[68:69]
	s_addc_u32 s25, s25, 0
	s_add_i32 s26, s64, s48
	global_load_lds_dwordx4 v[238:239], off
	v_lshl_add_u64 v[238:239], s[24:25], 0, v[148:149]
	s_mov_b32 m0, s26
	s_nop 0
	global_load_lds_dwordx4 v[238:239], off
	v_lshl_add_u64 v[238:239], s[24:25], 0, v[144:145]
	s_add_i32 m0, s26, 0x2000
	s_nop 0
	global_load_lds_dwordx4 v[238:239], off
	v_lshl_add_u64 v[238:239], s[20:21], 0, v[150:151]
	s_mov_b32 m0, s53
	s_nop 0
	global_load_lds_dwordx4 v[238:239], off
	v_lshl_add_u64 v[238:239], s[20:21], 0, v[146:147]
	s_mov_b32 m0, s54
	s_nop 0
	global_load_lds_dwordx4 v[238:239], off
	s_waitcnt vmcnt(8)
	s_waitcnt lgkmcnt(0)
	s_barrier
	s_setprio 1
	s_waitcnt lgkmcnt(0)
	v_mfma_f32_16x16x32_bf16 v[60:63], v[132:135], v[176:179], v[60:63]
	v_mfma_f32_16x16x32_bf16 v[56:59], v[140:143], v[176:179], v[56:59]
	v_mfma_f32_16x16x32_bf16 v[48:51], v[132:135], v[192:195], v[48:51]
	v_mfma_f32_16x16x32_bf16 v[40:43], v[140:143], v[192:195], v[40:43]
	v_mfma_f32_16x16x32_bf16 v[32:35], v[132:135], v[200:203], v[32:35]
	v_mfma_f32_16x16x32_bf16 v[24:27], v[140:143], v[200:203], v[24:27]
	v_mfma_f32_16x16x32_bf16 v[16:19], v[132:135], v[218:221], v[16:19]
	v_mfma_f32_16x16x32_bf16 v[8:11], v[140:143], v[218:221], v[8:11]
	v_mfma_f32_16x16x32_bf16 v[60:63], v[136:139], v[180:183], v[60:63]
	v_mfma_f32_16x16x32_bf16 v[56:59], v[156:159], v[180:183], v[56:59]
	v_mfma_f32_16x16x32_bf16 v[48:51], v[136:139], v[196:199], v[48:51]
	v_mfma_f32_16x16x32_bf16 v[40:43], v[156:159], v[196:199], v[40:43]
	v_mfma_f32_16x16x32_bf16 v[32:35], v[136:139], v[204:207], v[32:35]
	v_mfma_f32_16x16x32_bf16 v[24:27], v[156:159], v[204:207], v[24:27]
	v_mfma_f32_16x16x32_bf16 v[16:19], v[136:139], v[222:225], v[16:19]
	v_mfma_f32_16x16x32_bf16 v[8:11], v[156:159], v[222:225], v[8:11]
	s_setprio 0
	s_setprio 1
	v_mfma_f32_16x16x32_bf16 v[52:55], v[160:163], v[176:179], v[52:55]
	v_mfma_f32_16x16x32_bf16 v[44:47], v[168:171], v[176:179], v[44:47]
	v_mfma_f32_16x16x32_bf16 v[36:39], v[160:163], v[192:195], v[36:39]
	v_mfma_f32_16x16x32_bf16 v[28:31], v[168:171], v[192:195], v[28:31]
	v_mfma_f32_16x16x32_bf16 v[20:23], v[160:163], v[200:203], v[20:23]
	v_mfma_f32_16x16x32_bf16 v[12:15], v[168:171], v[200:203], v[12:15]
	v_mfma_f32_16x16x32_bf16 v[4:7], v[160:163], v[218:221], v[4:7]
	v_mfma_f32_16x16x32_bf16 v[0:3], v[168:171], v[218:221], v[0:3]
	v_mfma_f32_16x16x32_bf16 v[52:55], v[164:167], v[180:183], v[52:55]
	v_mfma_f32_16x16x32_bf16 v[44:47], v[172:175], v[180:183], v[44:47]
	v_mfma_f32_16x16x32_bf16 v[36:39], v[164:167], v[196:199], v[36:39]
	v_mfma_f32_16x16x32_bf16 v[28:31], v[172:175], v[196:199], v[28:31]
	v_mfma_f32_16x16x32_bf16 v[20:23], v[164:167], v[204:207], v[20:23]
	v_mfma_f32_16x16x32_bf16 v[12:15], v[172:175], v[204:207], v[12:15]
	v_mfma_f32_16x16x32_bf16 v[4:7], v[164:167], v[222:225], v[4:7]
	v_mfma_f32_16x16x32_bf16 v[0:3], v[172:175], v[222:225], v[0:3]
	s_setprio 0
	s_barrier
	s_add_i32 s62, s62, 2
	s_add_u32 s2, s2, 0x100
	s_addc_u32 s3, s3, 0
	s_cmp_gt_u32 s62, 13
	s_cbranch_scc0 .LBB0_702
	s_branch .Lpeel_exit_702
